# speedup vs baseline: 1.0353x; 1.0052x over previous
.LBB0_460:
	s_or_b64 exec, exec, s[0:1]
	s_add_u32 s0, s60, 0x1d800000
	s_addc_u32 s1, s61, 0
	v_writelane_b32 v252, s0, 44
	v_mov_b32_e32 v158, v218
	s_waitcnt lgkmcnt(0)
	v_writelane_b32 v252, s1, 45
	s_add_u32 s0, s60, 0x1e800000
	s_addc_u32 s1, s61, 0
	v_writelane_b32 v252, s0, 46
	s_cmpk_lt_i32 s70, 0x100
	s_barrier
	v_writelane_b32 v252, s1, 47
	s_cselect_b64 s[0:1], -1, 0
	v_writelane_b32 v252, s0, 48
	s_cmpk_gt_i32 s70, 0xff
	v_readfirstlane_b32 s6, v158
	v_writelane_b32 v252, s1, 49
	s_cbranch_scc1 .LBB0_490
	s_add_u32 s22, s60, 0x1d00000
	s_addc_u32 s23, s61, 0
	s_and_b32 s98, s70, 7
	s_lshr_b32 s99, s70, 3
	s_and_b32 s100, s99, 0x18
	s_lshl_b32 s100, s100, 2
	s_and_b32 s99, s99, 7
	s_or_b32 s99, s99, s100
	s_and_b32 s100, s98, 4
	s_lshl_b32 s100, s100, 5
	s_and_b32 s98, s98, 3
	s_lshl_b32 s98, s98, 3
	s_or_b32 s98, s98, s100
	s_or_b32 s98, s98, s99
	s_and_b32 s2, s98, 7
	s_bfe_u32 s3, s98, 0x20003
	s_cmpk_gt_u32 s98, 0x7f
	s_cbranch_scc0 .LBB0_464
	s_lshl_b32 s1, s3, 10
	s_lshl_b32 s4, s2, 20
	s_bfe_u32 s0, s98, 0x20005
	s_or_b32 s4, s1, s4
	s_add_u32 s16, s28, s4
	s_addc_u32 s17, s29, 0
	s_lshl_b32 s4, s0, 20
	s_or_b32 s1, s4, s1
	s_add_u32 s18, s78, s1
	s_addc_u32 s19, s79, 0
	s_lshl_b32 s0, s0, 3
	s_or_b32 s42, s0, s2
	s_cbranch_execz .LBB0_465
	s_mov_b32 s2, s3
	s_branch .LBB0_466
.LBB0_464:
.LBB0_465:
	s_lshr_b32 s0, s98, 5
	s_lshl_b32 s1, s3, 10
	s_lshl_b32 s4, s0, 20
	s_or_b32 s4, s1, s4
	s_add_u32 s16, s76, s4
	s_addc_u32 s17, s77, 0
	s_lshl_b32 s4, s2, 20
	s_or_b32 s1, s1, s4
	s_add_u32 s18, s22, s1
	s_addc_u32 s19, s23, 0
	s_lshl_b32 s0, s0, 2
	s_or_b32 s42, s0, s3

.LBB0_468:
	s_lshl_b32 s31, s4, 6
	s_lshl_b32 s7, s4, 13
	s_lshl_b32 s4, s5, 5
	s_and_b32 s33, s4, 0x60
	s_mov_b64 s[4:5], 0x80
	s_add_i32 m0, s24, 0x18000
	v_lshl_add_u64 v[6:7], v[6:7], 0, s[4:5]
	s_ashr_i32 s43, s98, 7
	s_lshl_b32 s10, s33, 7
	global_load_lds_dwordx4 v[6:7], off
	v_lshl_add_u64 v[4:5], v[4:5], 0, s[4:5]
	s_add_i32 m0, s24, 0x1a000
	s_add_i32 s34, s24, 0x8000
	s_add_i32 s35, s24, 0xa000
	global_load_lds_dwordx4 v[4:5], off
	v_lshl_add_u64 v[0:1], v[0:1], 0, s[4:5]
	s_mov_b32 m0, s34
	s_add_u32 s8, s18, 0x80080
	global_load_lds_dwordx4 v[0:1], off
	v_lshl_add_u64 v[0:1], v[2:3], 0, s[4:5]
	s_mov_b32 m0, s35
	s_addc_u32 s9, s19, 0
	global_load_lds_dwordx4 v[0:1], off
	s_add_i32 m0, s24, 0x1c000
	v_lshl_add_u64 v[0:1], s[8:9], 0, v[134:135]
	global_load_lds_dwordx4 v[0:1], off
	v_lshl_add_u64 v[0:1], s[8:9], 0, v[138:139]
	s_add_i32 m0, s24, 0x1e000
	s_movk_i32 s8, 0x3c0
	global_load_lds_dwordx4 v[0:1], off
	s_waitcnt vmcnt(8)
	s_barrier
	v_and_b32_e32 v0, 48, v158
	v_lshlrev_b32_e32 v1, 6, v158
	v_and_or_b32 v0, v1, s8, v0
	v_lshlrev_b32_e32 v1, 2, v158
	v_and_b32_e32 v1, 32, v1
	v_bitop3_b32 v2, v0, s7, v1 bitop3:0xde
	v_bitop3_b32 v159, s10, v0, v1 bitop3:0xf6
	v_lshlrev_b32_e32 v0, 15, v8
	v_and_b32_e32 v0, 0xffff0000, v0
	v_lshl_add_u32 v0, v9, 12, v0
	v_and_b32_e32 v1, 1, v8
	v_lshl_or_b32 v0, v1, 6, v0
	v_lshl_add_u32 v140, v10, 1, v0
	v_lshlrev_b32_e32 v0, 15, v11
	v_and_b32_e32 v0, 0xffff0000, v0
	s_waitcnt vmcnt(6)
	s_cmpk_lt_u32 s6, 0x100
	v_lshl_add_u32 v0, v12, 12, v0
	v_and_b32_e32 v1, 1, v11
	s_cselect_b64 s[6:7], -1, 0
	v_lshl_or_b32 v0, v1, 6, v0
	s_add_i32 s36, 0, 0x10000
	s_add_i32 s37, 0, 0x14000
	v_mov_b32_e32 v141, v135
	v_lshl_add_u32 v142, v13, 1, v0
	v_mov_b32_e32 v143, v135
	v_add_u32_e32 v160, s36, v159
	v_add_u32_e32 v161, s37, v159
	v_add_u32_e32 v162, 0, v2
	s_mov_b32 s38, 0xa0000
	s_mov_b64 s[8:9], 0xb0000
	s_mov_b32 s39, 0xb0000
	s_mov_b64 s[12:13], s[18:19]
	s_mov_b64 s[10:11], s[16:17]
	s_barrier
	s_branch .LBB0_471
